# P8 branch-A filler GEMM epilogue (acc*z): 16 z-row loads issued upfront into dead fragment VGPRs (ladder de-serialised)
# baseline (speedup 1.0000x reference)
; __device__ __forceinline__ float bflo(unsigned w) { return __uint_as_float(w << 16); }
;     __device__ __forceinline__ void operator()(const f32x4 (&acc)[2][2][4][2], const Unit& u, int wr, int wc, int fr, int fq) const {
;     ...
; #pragma unroll
;             for (int ai = 0; ai < 2; ++ai)
; #pragma unroll
;                 for (int m = 0; m < 4; ++m) {
;                     const int row = row0 + ai * HALF + m * 16;
; #pragma unroll
;                     for (int bj = 0; bj < 2; ++bj) {
;                         const int col = u.pn * BM + bj * HALF + wc * 32 + 8 * fq;
;                         f32x4 v0 = acc[ai][bj][m][0], v1 = acc[ai][bj][m][1];
;                         if constexpr (MODE == EM_WIN) {
;                             if (act == 1) { for (int j = 0; j < 4; ++j) { v0[j] = gelu_tanh_f(v0[j]); v1[j] = gelu_tanh_f(v1[j]); } }
;                             else if (act == 2) { for (int j = 0; j < 4; ++j) { v0[j] = __builtin_amdgcn_rcpf(1.f + __builtin_amdgcn_exp2f(v0[j])); v1[j] = __builtin_amdgcn_rcpf(1.f + __builtin_amdgcn_exp2f(v1[j])); } }
;                         }
;                         if constexpr (MODE == EM_SCALE) { v0 = v0 * scale; v1 = v1 * scale; }
;                         if constexpr (MODE == EM_MULZ || MODE == EM_FMAZ || MODE == EM_SIGMUL) {
;                             const u32x4 z = *(const u32x4*)(aux + (size_t)row * ldaux + col);
;                             f32x4 z0 = {bflo(z.x), bfhi(z.x), bflo(z.y), bfhi(z.y)}, z1 = {bflo(z.z), bfhi(z.z), bflo(z.w), bfhi(z.w)};
;                             if constexpr (MODE == EM_SIGMUL) { for (int j = 0; j < 4; ++j) { v0[j] = sigmoid_f(v0[j]); v1[j] = sigmoid_f(v1[j]); } }
;                             v0 = v0 * z0; v1 = v1 * z1;
;                             if constexpr (MODE == EM_FMAZ) {
;                                 const u32x4 y = *(const u32x4*)(add + (size_t)row * ldadd + col);
;                                 v0 += (f32x4){bflo(y.x), bfhi(y.x), bflo(y.y), bfhi(y.y)}; v1 += (f32x4){bflo(y.z), bfhi(y.z), bflo(y.w), bfhi(y.w)};
;                             }
;                         }
;                         u32x4 w; w.x = pk2(v0[0], v0[1]); w.y = pk2(v0[2], v0[3]); w.z = pk2(v1[0], v1[1]); w.w = pk2(v1[2], v1[3]);
;                         *(u32x4*)(O + (size_t)row * ldc + col) = w;
.LBB0_1454:
	s_lshl_b32 s2, s13, 8
	s_or_b32 s2, s20, s2
	v_or_b32_e32 v154, s2, v166
	v_readlane_b32 s2, v254, 37
	v_readlane_b32 s3, v254, 38
	v_lshl_add_u32 v158, s12, 8, v167
	s_movk_i32 s6, 0x2a00
	v_mov_b64_e32 v[156:157], s[2:3]
	v_ashrrev_i32_e32 v155, 31, v154
	v_mad_i64_i32 v[160:161], s[2:3], v158, s6, v[156:157]
	v_lshlrev_b64 v[154:155], 1, v[154:155]
	v_lshl_add_u64 v[166:167], v[160:161], 0, v[154:155]
	global_load_dwordx4 v[172:175], v[166:167], off offset:256
	s_mov_b32 s98, 0x2a000
	s_mov_b32 s99, 0
	v_lshl_add_u64 v[216:217], v[166:167], 0, s[98:99]
	global_load_dwordx4 v[176:179], v[216:217], off
	global_load_dwordx4 v[180:183], v[216:217], off offset:256
	s_mov_b32 s98, 0x54000
	s_mov_b32 s99, 0
	v_lshl_add_u64 v[216:217], v[166:167], 0, s[98:99]
	global_load_dwordx4 v[184:187], v[216:217], off
	global_load_dwordx4 v[188:191], v[216:217], off offset:256
	s_mov_b32 s98, 0x7e000
	s_mov_b32 s99, 0
	v_lshl_add_u64 v[216:217], v[166:167], 0, s[98:99]
	global_load_dwordx4 v[192:195], v[216:217], off
	global_load_dwordx4 v[196:199], v[216:217], off offset:256
	s_mov_b32 s98, 0x150000
	s_mov_b32 s99, 0
	v_lshl_add_u64 v[216:217], v[166:167], 0, s[98:99]
	global_load_dwordx4 v[200:203], v[216:217], off
	global_load_dwordx4 v[204:207], v[216:217], off offset:256
	s_mov_b32 s98, 0x17a000
	s_mov_b32 s99, 0
	v_lshl_add_u64 v[216:217], v[166:167], 0, s[98:99]
	global_load_dwordx4 v[208:211], v[216:217], off
	global_load_dwordx4 v[212:215], v[216:217], off offset:256
	s_mov_b32 s98, 0x1a4000
	s_mov_b32 s99, 0
	v_lshl_add_u64 v[216:217], v[166:167], 0, s[98:99]
	global_load_dwordx4 v[220:223], v[216:217], off
	global_load_dwordx4 v[226:229], v[216:217], off offset:256
	s_mov_b32 s98, 0x1ce000
	s_mov_b32 s99, 0
	v_lshl_add_u64 v[216:217], v[166:167], 0, s[98:99]
	global_load_dwordx4 v[230:233], v[216:217], off
	global_load_dwordx4 v[234:237], v[216:217], off offset:256
	global_load_dwordx4 v[160:163], v[166:167], off
	v_ashrrev_i32_e32 v159, 31, v158
	v_readlane_b32 s4, v254, 35
	v_readlane_b32 s5, v254, 36
	s_waitcnt vmcnt(0)
	v_lshlrev_b32_e32 v168, 16, v160
	v_and_b32_e32 v169, 0xffff0000, v160
	v_lshlrev_b32_e32 v160, 16, v161
	v_and_b32_e32 v161, 0xffff0000, v161
	v_lshlrev_b32_e32 v170, 16, v162
	v_and_b32_e32 v171, 0xffff0000, v162
	v_lshlrev_b32_e32 v162, 16, v163
	v_and_b32_e32 v163, 0xffff0000, v163
	v_pk_mul_f32 v[148:149], v[148:149], v[168:169]
	v_pk_mul_f32 v[150:151], v[150:151], v[160:161]
	v_pk_mul_f32 v[160:161], v[146:147], v[162:163]
	v_pk_mul_f32 v[146:147], v[144:145], v[170:171]
	v_cvt_pk_bf16_f32 v144, v148, v149
	v_lshlrev_b64 v[148:149], 11, v[158:159]
	v_lshl_add_u64 v[148:149], s[4:5], 0, v[148:149]
	v_cvt_pk_bf16_f32 v145, v150, v151
	v_cvt_pk_bf16_f32 v146, v146, v147
	v_cvt_pk_bf16_f32 v147, v160, v161
	v_lshl_add_u64 v[148:149], v[148:149], 0, v[154:155]
	global_store_dwordx4 v[148:149], v[144:147], off
	s_nop 1
	v_mov_b64_e32 v[144:145], v[172:173]
	v_mov_b64_e32 v[146:147], v[174:175]
	v_lshlrev_b32_e32 v150, 16, v144
	v_and_b32_e32 v151, 0xffff0000, v144
	v_lshlrev_b32_e32 v144, 16, v145
	v_and_b32_e32 v145, 0xffff0000, v145
	v_lshlrev_b32_e32 v160, 16, v146
	v_and_b32_e32 v161, 0xffff0000, v146
	v_lshlrev_b32_e32 v146, 16, v147
	v_and_b32_e32 v147, 0xffff0000, v147
	v_pk_mul_f32 v[142:143], v[142:143], v[144:145]
	v_pk_mul_f32 v[140:141], v[140:141], v[150:151]
	v_pk_mul_f32 v[144:145], v[138:139], v[146:147]
	v_pk_mul_f32 v[138:139], v[136:137], v[160:161]
	v_cvt_pk_bf16_f32 v136, v140, v141
	v_cvt_pk_bf16_f32 v137, v142, v143
	v_cvt_pk_bf16_f32 v138, v138, v139
	v_cvt_pk_bf16_f32 v139, v144, v145
	v_or_b32_e32 v140, 16, v158
	global_store_dwordx4 v[148:149], v[136:139], off offset:256
	v_ashrrev_i32_e32 v141, 31, v140
	s_nop 0
	v_mad_i64_i32 v[136:137], s[2:3], v140, s6, v[156:157]
	v_lshl_add_u64 v[142:143], v[136:137], 0, v[154:155]
	v_mov_b64_e32 v[136:137], v[176:177]
	v_mov_b64_e32 v[138:139], v[178:179]
	v_lshlrev_b32_e32 v144, 16, v136
	v_and_b32_e32 v145, 0xffff0000, v136
	v_lshlrev_b32_e32 v136, 16, v137
	v_and_b32_e32 v137, 0xffff0000, v137
	v_lshlrev_b32_e32 v146, 16, v138
	v_and_b32_e32 v147, 0xffff0000, v138
	v_lshlrev_b32_e32 v138, 16, v139
	v_and_b32_e32 v139, 0xffff0000, v139
	v_pk_mul_f32 v[132:133], v[132:133], v[144:145]
	v_pk_mul_f32 v[134:135], v[134:135], v[136:137]
	v_pk_mul_f32 v[136:137], v[130:131], v[138:139]
	v_pk_mul_f32 v[130:131], v[128:129], v[146:147]
	v_cvt_pk_bf16_f32 v128, v132, v133
	v_lshlrev_b64 v[132:133], 11, v[140:141]
	v_lshl_add_u64 v[132:133], s[4:5], 0, v[132:133]
	v_cvt_pk_bf16_f32 v129, v134, v135
	v_cvt_pk_bf16_f32 v130, v130, v131
	v_cvt_pk_bf16_f32 v131, v136, v137
	v_lshl_add_u64 v[132:133], v[132:133], 0, v[154:155]
	global_store_dwordx4 v[132:133], v[128:131], off
	s_nop 1
	v_mov_b64_e32 v[128:129], v[180:181]
	v_mov_b64_e32 v[130:131], v[182:183]
	v_lshlrev_b32_e32 v134, 16, v128
	v_and_b32_e32 v135, 0xffff0000, v128
	v_lshlrev_b32_e32 v128, 16, v129
	v_and_b32_e32 v129, 0xffff0000, v129
	v_lshlrev_b32_e32 v136, 16, v130
	v_and_b32_e32 v137, 0xffff0000, v130
	v_lshlrev_b32_e32 v130, 16, v131
	v_and_b32_e32 v131, 0xffff0000, v131
	v_pk_mul_f32 v[126:127], v[126:127], v[128:129]
	v_pk_mul_f32 v[124:125], v[124:125], v[134:135]
	v_pk_mul_f32 v[128:129], v[122:123], v[130:131]
	v_pk_mul_f32 v[122:123], v[120:121], v[136:137]
	v_cvt_pk_bf16_f32 v120, v124, v125
	v_cvt_pk_bf16_f32 v121, v126, v127
	v_cvt_pk_bf16_f32 v122, v122, v123
	v_cvt_pk_bf16_f32 v123, v128, v129
	v_or_b32_e32 v124, 32, v158
	global_store_dwordx4 v[132:133], v[120:123], off offset:256
	v_ashrrev_i32_e32 v125, 31, v124
	s_nop 0
	v_mad_i64_i32 v[120:121], s[2:3], v124, s6, v[156:157]
; __device__ __forceinline__ float bflo(unsigned w) { return __uint_as_float(w << 16); }
;     __device__ __forceinline__ void operator()(const f32x4 (&acc)[2][2][4][2], const Unit& u, int wr, int wc, int fr, int fq) const {
;     ...
; #pragma unroll
;             for (int ai = 0; ai < 2; ++ai)
; #pragma unroll
;                 for (int m = 0; m < 4; ++m) {
;                     const int row = row0 + ai * HALF + m * 16;
; #pragma unroll
;                     for (int bj = 0; bj < 2; ++bj) {
;                         const int col = u.pn * BM + bj * HALF + wc * 32 + 8 * fq;
;                         f32x4 v0 = acc[ai][bj][m][0], v1 = acc[ai][bj][m][1];
;                         if constexpr (MODE == EM_WIN) {
;                             if (act == 1) { for (int j = 0; j < 4; ++j) { v0[j] = gelu_tanh_f(v0[j]); v1[j] = gelu_tanh_f(v1[j]); } }
;                             else if (act == 2) { for (int j = 0; j < 4; ++j) { v0[j] = __builtin_amdgcn_rcpf(1.f + __builtin_amdgcn_exp2f(v0[j])); v1[j] = __builtin_amdgcn_rcpf(1.f + __builtin_amdgcn_exp2f(v1[j])); } }
;                         }
;                         if constexpr (MODE == EM_SCALE) { v0 = v0 * scale; v1 = v1 * scale; }
;                         if constexpr (MODE == EM_MULZ || MODE == EM_FMAZ || MODE == EM_SIGMUL) {
;                             const u32x4 z = *(const u32x4*)(aux + (size_t)row * ldaux + col);
;                             f32x4 z0 = {bflo(z.x), bfhi(z.x), bflo(z.y), bfhi(z.y)}, z1 = {bflo(z.z), bfhi(z.z), bflo(z.w), bfhi(z.w)};
;                             if constexpr (MODE == EM_SIGMUL) { for (int j = 0; j < 4; ++j) { v0[j] = sigmoid_f(v0[j]); v1[j] = sigmoid_f(v1[j]); } }
;                             v0 = v0 * z0; v1 = v1 * z1;
;                             if constexpr (MODE == EM_FMAZ) {
;                                 const u32x4 y = *(const u32x4*)(add + (size_t)row * ldadd + col);
;                                 v0 += (f32x4){bflo(y.x), bfhi(y.x), bflo(y.y), bfhi(y.y)}; v1 += (f32x4){bflo(y.z), bfhi(y.z), bflo(y.w), bfhi(y.w)};
;                             }
;                         }
;                         u32x4 w; w.x = pk2(v0[0], v0[1]); w.y = pk2(v0[2], v0[3]); w.z = pk2(v1[0], v1[1]); w.w = pk2(v1[2], v1[3]);
;                         *(u32x4*)(O + (size_t)row * ldc + col) = w;
	v_lshl_add_u64 v[126:127], v[120:121], 0, v[154:155]
	v_mov_b64_e32 v[120:121], v[184:185]
	v_mov_b64_e32 v[122:123], v[186:187]
	v_lshlrev_b32_e32 v128, 16, v120
	v_and_b32_e32 v129, 0xffff0000, v120
	v_lshlrev_b32_e32 v120, 16, v121
	v_and_b32_e32 v121, 0xffff0000, v121
	v_lshlrev_b32_e32 v130, 16, v122
	v_and_b32_e32 v131, 0xffff0000, v122
	v_lshlrev_b32_e32 v122, 16, v123
	v_and_b32_e32 v123, 0xffff0000, v123
	v_pk_mul_f32 v[116:117], v[116:117], v[128:129]
	v_pk_mul_f32 v[118:119], v[118:119], v[120:121]
	v_pk_mul_f32 v[120:121], v[114:115], v[122:123]
	v_pk_mul_f32 v[114:115], v[112:113], v[130:131]
	v_cvt_pk_bf16_f32 v112, v116, v117
	v_lshlrev_b64 v[116:117], 11, v[124:125]
	v_lshl_add_u64 v[116:117], s[4:5], 0, v[116:117]
	v_cvt_pk_bf16_f32 v113, v118, v119
	v_cvt_pk_bf16_f32 v114, v114, v115
	v_cvt_pk_bf16_f32 v115, v120, v121
	v_lshl_add_u64 v[116:117], v[116:117], 0, v[154:155]
	global_store_dwordx4 v[116:117], v[112:115], off
	s_nop 1
	v_mov_b64_e32 v[112:113], v[188:189]
	v_mov_b64_e32 v[114:115], v[190:191]
	v_lshlrev_b32_e32 v118, 16, v112
	v_and_b32_e32 v119, 0xffff0000, v112
	v_lshlrev_b32_e32 v112, 16, v113
	v_and_b32_e32 v113, 0xffff0000, v113
	v_lshlrev_b32_e32 v120, 16, v114
	v_and_b32_e32 v121, 0xffff0000, v114
	v_lshlrev_b32_e32 v114, 16, v115
	v_and_b32_e32 v115, 0xffff0000, v115
	v_pk_mul_f32 v[110:111], v[110:111], v[112:113]
	v_pk_mul_f32 v[108:109], v[108:109], v[118:119]
	v_pk_mul_f32 v[112:113], v[106:107], v[114:115]
	v_pk_mul_f32 v[106:107], v[104:105], v[120:121]
	v_cvt_pk_bf16_f32 v104, v108, v109
	v_cvt_pk_bf16_f32 v105, v110, v111
	v_cvt_pk_bf16_f32 v106, v106, v107
	v_cvt_pk_bf16_f32 v107, v112, v113
	v_or_b32_e32 v108, 48, v158
	global_store_dwordx4 v[116:117], v[104:107], off offset:256
	v_ashrrev_i32_e32 v109, 31, v108
	s_nop 0
	v_mad_i64_i32 v[104:105], s[2:3], v108, s6, v[156:157]
	v_lshl_add_u64 v[110:111], v[104:105], 0, v[154:155]
	v_mov_b64_e32 v[104:105], v[192:193]
	v_mov_b64_e32 v[106:107], v[194:195]
	v_lshlrev_b32_e32 v112, 16, v104
	v_and_b32_e32 v113, 0xffff0000, v104
	v_lshlrev_b32_e32 v104, 16, v105
	v_and_b32_e32 v105, 0xffff0000, v105
	v_lshlrev_b32_e32 v114, 16, v106
	v_and_b32_e32 v115, 0xffff0000, v106
	v_lshlrev_b32_e32 v106, 16, v107
	v_and_b32_e32 v107, 0xffff0000, v107
	v_pk_mul_f32 v[76:77], v[76:77], v[112:113]
	v_pk_mul_f32 v[78:79], v[78:79], v[104:105]
	v_pk_mul_f32 v[104:105], v[74:75], v[106:107]
	v_pk_mul_f32 v[74:75], v[72:73], v[114:115]
	v_cvt_pk_bf16_f32 v72, v76, v77
	v_lshlrev_b64 v[76:77], 11, v[108:109]
	v_lshl_add_u64 v[76:77], s[4:5], 0, v[76:77]
	v_cvt_pk_bf16_f32 v73, v78, v79
	v_cvt_pk_bf16_f32 v74, v74, v75
	v_cvt_pk_bf16_f32 v75, v104, v105
	v_lshl_add_u64 v[76:77], v[76:77], 0, v[154:155]
	global_store_dwordx4 v[76:77], v[72:75], off
	s_nop 1
	v_mov_b64_e32 v[72:73], v[196:197]
	v_mov_b64_e32 v[74:75], v[198:199]
	v_lshlrev_b32_e32 v78, 16, v72
	v_and_b32_e32 v79, 0xffff0000, v72
	v_lshlrev_b32_e32 v72, 16, v73
	v_and_b32_e32 v73, 0xffff0000, v73
	v_lshlrev_b32_e32 v104, 16, v74
	v_and_b32_e32 v105, 0xffff0000, v74
	v_lshlrev_b32_e32 v74, 16, v75
	v_and_b32_e32 v75, 0xffff0000, v75
	v_pk_mul_f32 v[70:71], v[70:71], v[72:73]
	v_pk_mul_f32 v[68:69], v[68:69], v[78:79]
	v_pk_mul_f32 v[72:73], v[66:67], v[74:75]
	v_pk_mul_f32 v[66:67], v[64:65], v[104:105]
	v_cvt_pk_bf16_f32 v64, v68, v69
	v_cvt_pk_bf16_f32 v65, v70, v71
	v_cvt_pk_bf16_f32 v66, v66, v67
	v_cvt_pk_bf16_f32 v67, v72, v73
	v_add_u32_e32 v68, 0x80, v158
	global_store_dwordx4 v[76:77], v[64:67], off offset:256
	v_ashrrev_i32_e32 v69, 31, v68
	s_nop 0
	v_mad_i64_i32 v[64:65], s[2:3], v68, s6, v[156:157]
	v_lshl_add_u64 v[70:71], v[64:65], 0, v[154:155]
	v_mov_b64_e32 v[64:65], v[200:201]
	v_mov_b64_e32 v[66:67], v[202:203]
	v_lshlrev_b32_e32 v72, 16, v64
	v_and_b32_e32 v73, 0xffff0000, v64
	v_lshlrev_b32_e32 v64, 16, v65
	v_and_b32_e32 v65, 0xffff0000, v65
	v_lshlrev_b32_e32 v74, 16, v66
	v_and_b32_e32 v75, 0xffff0000, v66
	v_lshlrev_b32_e32 v66, 16, v67
	v_and_b32_e32 v67, 0xffff0000, v67
	v_pk_mul_f32 v[60:61], v[60:61], v[72:73]
	v_pk_mul_f32 v[62:63], v[62:63], v[64:65]
	v_pk_mul_f32 v[64:65], v[58:59], v[66:67]
	v_pk_mul_f32 v[58:59], v[56:57], v[74:75]
	v_cvt_pk_bf16_f32 v56, v60, v61
	v_lshlrev_b64 v[60:61], 11, v[68:69]
	v_lshl_add_u64 v[60:61], s[4:5], 0, v[60:61]
	v_cvt_pk_bf16_f32 v57, v62, v63
	v_cvt_pk_bf16_f32 v58, v58, v59
	v_cvt_pk_bf16_f32 v59, v64, v65
	v_lshl_add_u64 v[60:61], v[60:61], 0, v[154:155]
	global_store_dwordx4 v[60:61], v[56:59], off
	s_nop 1
	v_mov_b64_e32 v[56:57], v[204:205]
	v_mov_b64_e32 v[58:59], v[206:207]
	v_lshlrev_b32_e32 v62, 16, v56
	v_and_b32_e32 v63, 0xffff0000, v56
	v_lshlrev_b32_e32 v56, 16, v57
	v_and_b32_e32 v57, 0xffff0000, v57
	v_lshlrev_b32_e32 v64, 16, v58
	v_and_b32_e32 v65, 0xffff0000, v58
	v_lshlrev_b32_e32 v58, 16, v59
	v_and_b32_e32 v59, 0xffff0000, v59
	v_pk_mul_f32 v[54:55], v[54:55], v[56:57]
	v_pk_mul_f32 v[52:53], v[52:53], v[62:63]
	v_pk_mul_f32 v[56:57], v[50:51], v[58:59]
	v_pk_mul_f32 v[50:51], v[48:49], v[64:65]
	v_cvt_pk_bf16_f32 v48, v52, v53
	v_cvt_pk_bf16_f32 v49, v54, v55
	v_cvt_pk_bf16_f32 v50, v50, v51
	v_cvt_pk_bf16_f32 v51, v56, v57
	v_add_u32_e32 v52, 0x90, v158
	global_store_dwordx4 v[60:61], v[48:51], off offset:256
	v_ashrrev_i32_e32 v53, 31, v52
	s_nop 0
	v_mad_i64_i32 v[48:49], s[2:3], v52, s6, v[156:157]
	v_lshl_add_u64 v[54:55], v[48:49], 0, v[154:155]
	v_mov_b64_e32 v[48:49], v[208:209]
	v_mov_b64_e32 v[50:51], v[210:211]
	v_lshlrev_b32_e32 v56, 16, v48
; #define LAS __attribute__((address_space(3)))
;     __device__ __forceinline__ void operator()(const f32x4 (&acc)[2][2][4][2], const Unit& u, int wr, int wc, int fr, int fq) const {
;     ...
; #pragma unroll
;             for (int ai = 0; ai < 2; ++ai)
; #pragma unroll
;                 for (int m = 0; m < 4; ++m) {
;                     const int row = row0 + ai * HALF + m * 16;
; #pragma unroll
;                     for (int bj = 0; bj < 2; ++bj) {
;                         const int col = u.pn * BM + bj * HALF + wc * 32 + 8 * fq;
;                         f32x4 v0 = acc[ai][bj][m][0], v1 = acc[ai][bj][m][1];
;                         if constexpr (MODE == EM_WIN) {
;                             if (act == 1) { for (int j = 0; j < 4; ++j) { v0[j] = gelu_tanh_f(v0[j]); v1[j] = gelu_tanh_f(v1[j]); } }
;                             else if (act == 2) { for (int j = 0; j < 4; ++j) { v0[j] = __builtin_amdgcn_rcpf(1.f + __builtin_amdgcn_exp2f(v0[j])); v1[j] = __builtin_amdgcn_rcpf(1.f + __builtin_amdgcn_exp2f(v1[j])); } }
;                         }
;                         if constexpr (MODE == EM_SCALE) { v0 = v0 * scale; v1 = v1 * scale; }
;                         if constexpr (MODE == EM_MULZ || MODE == EM_FMAZ || MODE == EM_SIGMUL) {
;                             const u32x4 z = *(const u32x4*)(aux + (size_t)row * ldaux + col);
;                             f32x4 z0 = {bflo(z.x), bfhi(z.x), bflo(z.y), bfhi(z.y)}, z1 = {bflo(z.z), bfhi(z.z), bflo(z.w), bfhi(z.w)};
;                             if constexpr (MODE == EM_SIGMUL) { for (int j = 0; j < 4; ++j) { v0[j] = sigmoid_f(v0[j]); v1[j] = sigmoid_f(v1[j]); } }
;                             v0 = v0 * z0; v1 = v1 * z1;
;                             if constexpr (MODE == EM_FMAZ) {
;                                 const u32x4 y = *(const u32x4*)(add + (size_t)row * ldadd + col);
;                                 v0 += (f32x4){bflo(y.x), bfhi(y.x), bflo(y.y), bfhi(y.y)}; v1 += (f32x4){bflo(y.z), bfhi(y.z), bflo(y.w), bfhi(y.w)};
;                             }
;                         }
;                         u32x4 w; w.x = pk2(v0[0], v0[1]); w.y = pk2(v0[2], v0[3]); w.z = pk2(v1[0], v1[1]); w.w = pk2(v1[2], v1[3]);
;                         *(u32x4*)(O + (size_t)row * ldc + col) = w;
; __device__ __forceinline__ int q_grab(unsigned* que, LAS int* slot, int wv) {
	v_and_b32_e32 v57, 0xffff0000, v48
	v_lshlrev_b32_e32 v48, 16, v49
	v_and_b32_e32 v49, 0xffff0000, v49
	v_lshlrev_b32_e32 v58, 16, v50
	v_and_b32_e32 v59, 0xffff0000, v50
	v_lshlrev_b32_e32 v50, 16, v51
	v_and_b32_e32 v51, 0xffff0000, v51
	v_pk_mul_f32 v[44:45], v[44:45], v[56:57]
	v_pk_mul_f32 v[46:47], v[46:47], v[48:49]
	v_pk_mul_f32 v[48:49], v[42:43], v[50:51]
	v_pk_mul_f32 v[42:43], v[40:41], v[58:59]
	v_cvt_pk_bf16_f32 v40, v44, v45
	v_lshlrev_b64 v[44:45], 11, v[52:53]
	v_lshl_add_u64 v[44:45], s[4:5], 0, v[44:45]
	v_cvt_pk_bf16_f32 v41, v46, v47
	v_cvt_pk_bf16_f32 v42, v42, v43
	v_cvt_pk_bf16_f32 v43, v48, v49
	v_lshl_add_u64 v[44:45], v[44:45], 0, v[154:155]
	global_store_dwordx4 v[44:45], v[40:43], off
	s_nop 1
	v_mov_b64_e32 v[40:41], v[212:213]
	v_mov_b64_e32 v[42:43], v[214:215]
	v_lshlrev_b32_e32 v46, 16, v40
	v_and_b32_e32 v47, 0xffff0000, v40
	v_lshlrev_b32_e32 v40, 16, v41
	v_and_b32_e32 v41, 0xffff0000, v41
	v_lshlrev_b32_e32 v48, 16, v42
	v_and_b32_e32 v49, 0xffff0000, v42
	v_lshlrev_b32_e32 v42, 16, v43
	v_and_b32_e32 v43, 0xffff0000, v43
	v_pk_mul_f32 v[38:39], v[38:39], v[40:41]
	v_pk_mul_f32 v[36:37], v[36:37], v[46:47]
	v_pk_mul_f32 v[40:41], v[34:35], v[42:43]
	v_pk_mul_f32 v[34:35], v[32:33], v[48:49]
	v_cvt_pk_bf16_f32 v32, v36, v37
	v_cvt_pk_bf16_f32 v33, v38, v39
	v_cvt_pk_bf16_f32 v34, v34, v35
	v_cvt_pk_bf16_f32 v35, v40, v41
	v_add_u32_e32 v36, 0xa0, v158
	global_store_dwordx4 v[44:45], v[32:35], off offset:256
	v_ashrrev_i32_e32 v37, 31, v36
	s_nop 0
	v_mad_i64_i32 v[32:33], s[2:3], v36, s6, v[156:157]
	v_lshl_add_u64 v[38:39], v[32:33], 0, v[154:155]
	v_mov_b64_e32 v[32:33], v[220:221]
	v_mov_b64_e32 v[34:35], v[222:223]
	v_lshlrev_b32_e32 v40, 16, v32
	v_and_b32_e32 v41, 0xffff0000, v32
	v_lshlrev_b32_e32 v32, 16, v33
	v_and_b32_e32 v33, 0xffff0000, v33
	v_lshlrev_b32_e32 v42, 16, v34
	v_and_b32_e32 v43, 0xffff0000, v34
	v_lshlrev_b32_e32 v34, 16, v35
	v_and_b32_e32 v35, 0xffff0000, v35
	v_pk_mul_f32 v[28:29], v[28:29], v[40:41]
	v_pk_mul_f32 v[30:31], v[30:31], v[32:33]
	v_pk_mul_f32 v[32:33], v[26:27], v[34:35]
	v_pk_mul_f32 v[26:27], v[24:25], v[42:43]
	v_cvt_pk_bf16_f32 v24, v28, v29
	v_lshlrev_b64 v[28:29], 11, v[36:37]
	v_lshl_add_u64 v[28:29], s[4:5], 0, v[28:29]
	v_cvt_pk_bf16_f32 v25, v30, v31
	v_cvt_pk_bf16_f32 v26, v26, v27
	v_cvt_pk_bf16_f32 v27, v32, v33
	v_lshl_add_u64 v[28:29], v[28:29], 0, v[154:155]
	global_store_dwordx4 v[28:29], v[24:27], off
	s_nop 1
	v_mov_b64_e32 v[24:25], v[226:227]
	v_mov_b64_e32 v[26:27], v[228:229]
	v_lshlrev_b32_e32 v30, 16, v24
	v_and_b32_e32 v31, 0xffff0000, v24
	v_lshlrev_b32_e32 v24, 16, v25
	v_and_b32_e32 v25, 0xffff0000, v25
	v_lshlrev_b32_e32 v32, 16, v26
	v_and_b32_e32 v33, 0xffff0000, v26
	v_lshlrev_b32_e32 v26, 16, v27
	v_and_b32_e32 v27, 0xffff0000, v27
	v_pk_mul_f32 v[22:23], v[22:23], v[24:25]
	v_pk_mul_f32 v[20:21], v[20:21], v[30:31]
	v_pk_mul_f32 v[24:25], v[18:19], v[26:27]
	v_pk_mul_f32 v[18:19], v[16:17], v[32:33]
	v_cvt_pk_bf16_f32 v16, v20, v21
	v_cvt_pk_bf16_f32 v17, v22, v23
	v_cvt_pk_bf16_f32 v18, v18, v19
	v_cvt_pk_bf16_f32 v19, v24, v25
	v_add_u32_e32 v22, 0xb0, v158
	global_store_dwordx4 v[28:29], v[16:19], off offset:256
	v_ashrrev_i32_e32 v23, 31, v22
	s_nop 0
	v_mad_i64_i32 v[16:17], s[2:3], v22, s6, v[156:157]
	v_lshl_add_u64 v[16:17], v[16:17], 0, v[154:155]
	v_mov_b64_e32 v[18:19], v[230:231]
	v_mov_b64_e32 v[20:21], v[232:233]
	v_readlane_b32 s2, v254, 9
	s_cmp_ge_i32 s76, s2
	s_mov_b32 s6, s76
	v_lshlrev_b32_e32 v24, 16, v18
	v_and_b32_e32 v25, 0xffff0000, v18
	v_lshlrev_b32_e32 v18, 16, v19
	v_and_b32_e32 v19, 0xffff0000, v19
	v_lshlrev_b32_e32 v26, 16, v20
	v_and_b32_e32 v27, 0xffff0000, v20
	v_lshlrev_b32_e32 v20, 16, v21
	v_and_b32_e32 v21, 0xffff0000, v21
	v_pk_mul_f32 v[12:13], v[12:13], v[24:25]
	v_pk_mul_f32 v[14:15], v[14:15], v[18:19]
	v_pk_mul_f32 v[18:19], v[10:11], v[20:21]
	v_pk_mul_f32 v[10:11], v[8:9], v[26:27]
	v_cvt_pk_bf16_f32 v8, v12, v13
	v_lshlrev_b64 v[12:13], 11, v[22:23]
	v_lshl_add_u64 v[12:13], s[4:5], 0, v[12:13]
	v_cvt_pk_bf16_f32 v9, v14, v15
	v_cvt_pk_bf16_f32 v10, v10, v11
	v_cvt_pk_bf16_f32 v11, v18, v19
	v_lshl_add_u64 v[12:13], v[12:13], 0, v[154:155]
	global_store_dwordx4 v[12:13], v[8:11], off
	s_nop 1
	v_mov_b64_e32 v[8:9], v[234:235]
	v_mov_b64_e32 v[10:11], v[236:237]
	v_lshlrev_b32_e32 v14, 16, v8
	v_and_b32_e32 v15, 0xffff0000, v8
	v_lshlrev_b32_e32 v8, 16, v9
	v_and_b32_e32 v9, 0xffff0000, v9
	v_lshlrev_b32_e32 v16, 16, v10
	v_and_b32_e32 v17, 0xffff0000, v10
	v_lshlrev_b32_e32 v10, 16, v11
	v_and_b32_e32 v11, 0xffff0000, v11
	v_pk_mul_f32 v[6:7], v[6:7], v[8:9]
	v_pk_mul_f32 v[4:5], v[4:5], v[14:15]
	v_pk_mul_f32 v[8:9], v[2:3], v[10:11]
	v_pk_mul_f32 v[2:3], v[0:1], v[16:17]
	v_cvt_pk_bf16_f32 v0, v4, v5
	v_cvt_pk_bf16_f32 v1, v6, v7
	v_cvt_pk_bf16_f32 v2, v2, v3
	v_cvt_pk_bf16_f32 v3, v8, v9
	global_store_dwordx4 v[12:13], v[0:3], off offset:256
	s_waitcnt vmcnt(0)
	s_barrier
	s_cbranch_scc1 .LBB0_1395
	s_mov_b64 s[2:3], exec
	v_readlane_b32 s4, v254, 7
	v_readlane_b32 s5, v254, 8
	s_and_b64 s[4:5], s[2:3], s[4:5]
	s_mov_b64 exec, s[4:5]
	s_cbranch_execz .LBB0_1394
	s_mov_b64 s[6:7], exec
	v_mbcnt_lo_u32_b32 v0, s6, 0
	v_mbcnt_hi_u32_b32 v0, s7, v0
	v_cmp_eq_u32_e32 vcc, 0, v0
	s_and_saveexec_b64 s[4:5], vcc
	s_cbranch_execz .LBB0_1393
	s_bcnt1_i32_b64 s6, s[6:7]
	v_mov_b32_e32 v1, s6
	v_readlane_b32 s6, v254, 5
	v_readlane_b32 s7, v254, 6
	s_nop 4
	global_atomic_add v1, v153, v1, s[6:7] sc0
	s_branch .LBB0_1393
